# weight transposes spread more evenly over the residual GEMM tails (w_dn[1] and o_out one tail earlier)
# baseline (speedup 1.0000x reference)
; __global__ void __launch_bounds__(NTHREADS) mega_fwd(P p) {
;     ...
;                     const int nbusy = (RM / 256) * 4 - G;
;                     const unsigned tmask = cs == 0 ? 0x300u : (cs == 1 ? 0x022u : (cs == 2 ? 0x044u : (cs == 3 ? 0xC88u : 0u)));
;                     if (tmask && nbusy > 0 && nbusy < G && (int)blockIdx.x >= nbusy) { __syncthreads(); run_transposes(q, lds, wave, lane, tmask, ((int)blockIdx.x - nbusy) * 8 + wave, (G - nbusy) * 8); }
;                     else if (tmask && !(nbusy > 0 && nbusy < G)) { __syncthreads(); run_transposes(q, lds, wave, lane, tmask, (int)blockIdx.x * 8 + wave, G * 8); }
.LBB0_858:
	v_readlane_b32 s6, v255, 4
	s_cmp_lt_i32 s6, 1
	s_movk_i32 s30, 0x320
	s_waitcnt lgkmcnt(0)
	v_readlane_b32 s24, v255, 5
	s_cbranch_scc1 .LBB0_867
	s_cmp_lt_i32 s6, 2
	s_mov_b64 s[2:3], -1
	s_cbranch_scc1 .LBB0_865
	s_cmp_eq_u32 s6, 2
	s_cbranch_scc1 .LBB0_862
	s_cmp_eq_u32 s6, 3
	s_cselect_b32 s30, 0x488, 0
	s_mov_b64 s[2:3], 0
.LBB0_862:
	s_andn2_b64 vcc, exec, s[2:3]
	s_cbranch_vccnz .LBB0_864
	s_movk_i32 s30, 0x844

; __global__ void __launch_bounds__(NTHREADS) mega_fwd(P p) {
;     ...
;                     const unsigned tmask = cs == 0 ? 0x300u : (cs == 1 ? 0x022u : (cs == 2 ? 0x044u : (cs == 3 ? 0xC88u : 0u)));
.LBB0_865:
	s_andn2_b64 vcc, exec, s[2:3]
	s_cbranch_vccnz .LBB0_867
	s_mov_b32 s30, 2
